# kernel entry: the three x16 kernarg scalar loads issued together at the entry instead of in two later waves
# speedup vs baseline: 1.0019x; 1.0019x over previous
_Z14fwd_megakernel6Params:
	s_load_dwordx2 s[74:75], s[0:1], 0xd0
	s_load_dwordx4 s[92:95], s[0:1], 0xc0
	s_load_dword s90, s[0:1], 0xd8
	s_load_dwordx16 s[52:67], s[0:1], 0x0
	s_load_dwordx16 s[16:31], s[0:1], 0x40
	s_load_dwordx16 s[36:51], s[0:1], 0x80
	s_mov_b32 s14, s2
	s_add_u32 s2, s0, 0xd8
	s_addc_u32 s3, s1, 0
	v_readfirstlane_b32 s72, v0
	v_writelane_b32 v254, s2, 0
	v_cmp_eq_u32_e64 s[4:5], 0, v0
	s_nop 0
	v_writelane_b32 v254, s3, 1
	s_mov_b64 s[2:3], exec
	v_writelane_b32 v254, s4, 2
	s_nop 1
	v_writelane_b32 v254, s5, 3
	s_and_b64 s[4:5], s[2:3], s[4:5]
	s_mov_b64 exec, s[4:5]
	s_cbranch_execz .LBB0_2
	s_add_i32 s4, 0, 0x21fe0
	v_mov_b32_e32 v1, 0
	v_mov_b32_e32 v2, s4
	s_add_i32 s4, 0, 0x21fe4
	ds_write_b32 v2, v1
	v_mov_b32_e32 v2, s4
	ds_write_b32 v2, v1
.LBB0_2:
	s_or_b64 exec, exec, s[2:3]
	s_waitcnt lgkmcnt(0)
	s_barrier
	s_getreg_b32 s2, hwreg(HW_REG_XCC_ID, 0, 4)
	s_and_b32 s2, s2, 15
	v_writelane_b32 v254, s2, 4
	s_mov_b64 s[2:3], exec
	v_readlane_b32 s4, v254, 2
	v_readlane_b32 s5, v254, 3
	s_and_b64 s[4:5], s[2:3], s[4:5]
	s_mov_b64 exec, s[4:5]
	s_cbranch_execz .LBB0_5
	s_mov_b64 s[4:5], exec
	v_mbcnt_lo_u32_b32 v1, s4, 0
	v_mbcnt_hi_u32_b32 v1, s5, v1
	v_cmp_eq_u32_e32 vcc, 0, v1
	s_and_b64 s[6:7], exec, vcc
	s_mov_b64 exec, s[6:7]
	s_cbranch_execz .LBB0_5
	v_readlane_b32 s6, v254, 4
	s_lshl_b32 s6, s6, 8
	s_bcnt1_i32_b64 s4, s[4:5]
	v_mov_b32_e32 v1, s6
	v_mov_b32_e32 v2, s4
	global_atomic_add v1, v2, s[74:75] offset:1024
.LBB0_5:
	s_or_b64 exec, exec, s[2:3]
	v_and_b32_e32 v6, 7, v0
	v_lshlrev_b32_e32 v3, 12, v6
	s_add_i32 s73, 0, 0x11000
	s_waitcnt lgkmcnt(0)
	v_writelane_b32 v254, s16, 5
	v_or_b32_e32 v1, 0x200, v0
	v_add_u32_e32 v7, s73, v3
	v_writelane_b32 v254, s17, 6
	v_writelane_b32 v254, s18, 7
	v_writelane_b32 v254, s19, 8
	v_writelane_b32 v254, s20, 9
	v_writelane_b32 v254, s21, 10
	v_writelane_b32 v254, s22, 11
	v_writelane_b32 v254, s23, 12
	v_writelane_b32 v254, s24, 13
	v_writelane_b32 v254, s25, 14
	v_writelane_b32 v254, s26, 15
	v_writelane_b32 v254, s27, 16
	v_writelane_b32 v254, s28, 17
	v_writelane_b32 v254, s29, 18
	v_writelane_b32 v254, s30, 19
	v_writelane_b32 v254, s31, 20
	v_writelane_b32 v254, s36, 21
	v_or_b32_e32 v2, 0x1800, v6
	v_mov_b32_e32 v8, 8
	v_writelane_b32 v254, s37, 22
	v_writelane_b32 v254, s38, 23
	v_writelane_b32 v254, s39, 24
	v_writelane_b32 v254, s40, 25
	v_writelane_b32 v254, s41, 26
	v_writelane_b32 v254, s42, 27
	v_writelane_b32 v254, s43, 28
	v_writelane_b32 v254, s44, 29
	v_writelane_b32 v254, s45, 30
	v_writelane_b32 v254, s46, 31
	v_writelane_b32 v254, s47, 32
	v_writelane_b32 v254, s48, 33
	v_writelane_b32 v254, s49, 34
	v_writelane_b32 v254, s50, 35
	s_mov_b64 s[0:1], 0
	s_movk_i32 s2, 0x2008
	v_mov_b32_e32 v9, 0
	v_mov_b64_e32 v[4:5], v[0:1]
	v_writelane_b32 v254, s51, 36
